# tile remap + L2 prefetch of the residual tile right before the out-proj epilogue
# speedup vs baseline: 1.0020x; 1.0020x over previous
; template <int MODE, bool SWAP, int MT>
; DI void gemm_tile(const int wv_, const Params& p, const u16* __restrict__ A, const u16* __restrict__ Bt, int brow, int bcol, char* smem, const float* gnext) {
;     ...
;   for (int t = 0; t < 32; ++t) {
;     asm volatile("s_waitcnt vmcnt(0)" ::: "memory");
;     __syncthreads();
;     if (t + 1 < 32) stage(t + 1, (t + 1) & 1);
;     const char* sA = smem + (t & 1) * 24576; const char* sB = sA + 16384;
;     bf16x8 Af[MT], Bf[4];
; #pragma unroll
;     for (int n = 0; n < 4; ++n) Bf[n] = *(const bf16x8*)(sB + (wc * 64 + n * 16 + fr) * 64 + fq * 16);
;     constexpr int MH = MT >= 2 ? MT / 2 : 1;
; #pragma unroll
;     for (int m = 0; m < MH; ++m) Af[m] = *(const bf16x8*)(sA + (wr * (16 * MT) + m * 16 + fr) * 64 + fq * 16);
;     __builtin_amdgcn_sched_barrier(0);
; #pragma unroll
;     for (int m = MH; m < MT; ++m) Af[m] = *(const bf16x8*)(sA + (wr * (16 * MT) + m * 16 + fr) * 64 + fq * 16);
; #pragma unroll
;     for (int m = 0; m < MH; ++m)
; #pragma unroll
;       for (int n = 0; n < 4; ++n)
;         acc[m][n] = SWAP ? __builtin_amdgcn_mfma_f32_16x16x32_bf16(Bf[n], Af[m], acc[m][n], 0, 0, 0)
;                          : __builtin_amdgcn_mfma_f32_16x16x32_bf16(Af[m], Bf[n], acc[m][n], 0, 0, 0);
;     __builtin_amdgcn_sched_barrier(0);
; #pragma unroll
;     for (int m = MH; m < MT; ++m)
; #pragma unroll
;       for (int n = 0; n < 4; ++n)
;         acc[m][n] = SWAP ? __builtin_amdgcn_mfma_f32_16x16x32_bf16(Bf[n], Af[m], acc[m][n], 0, 0, 0)
;                          : __builtin_amdgcn_mfma_f32_16x16x32_bf16(Af[m], Bf[n], acc[m][n], 0, 0, 0);
;   }
;   __syncthreads();
;   if (SWAP) {
; #pragma unroll
;     for (int m = 0; m < MT; ++m) {
;       int R = brow + wr * (16 * MT) + m * 16 + fr;
;       if (MODE == 2) {
;         int b = R / P, pos = R - b * P;
;         const bool valid = pos >= 112;
;         float* hr = valid ? hrow(p, b, pos) : nullptr;
.LBB0_829:
	s_add_i32 s2, s1, 1
	s_bitcmp1_b32 s2, 0
	s_cselect_b32 s3, 0x6000, 0
	v_add_u32_e32 v2, s3, v74
	v_add_u32_e32 v80, 0x2000, v2
	v_readfirstlane_b32 s3, v2
	s_mov_b32 m0, s3
	v_readfirstlane_b32 s3, v80
	v_add_u32_e32 v2, 0x4000, v2
	s_waitcnt vmcnt(0)
	s_waitcnt vmcnt(0) lgkmcnt(0)
	s_barrier
	global_load_lds_dwordx4 v[0:1], off
	s_mov_b32 m0, s3
	v_readfirstlane_b32 s3, v2
	global_load_lds_dwordx4 v[68:69], off
	s_mov_b32 m0, s3
	s_bitcmp1_b32 s1, 0
	global_load_lds_dwordx4 v[70:71], off
	s_cselect_b32 s1, 0x6000, 0
	v_or_b32_e32 v2, s1, v75
	v_add_u32_e32 v92, v2, v78
	ds_read_b128 v[80:83], v92 offset:16384
	ds_read_b128 v[84:87], v92 offset:17408
	ds_read_b128 v[88:91], v92 offset:18432
	ds_read_b128 v[92:95], v92 offset:19456
	v_add_u32_e32 v2, v2, v79
	ds_read_b128 v[96:99], v2
	ds_read_b128 v[100:103], v2 offset:1024
	s_waitcnt lgkmcnt(0)
	v_mfma_f32_16x16x32_bf16 v[64:67], v[80:83], v[96:99], v[64:67]
	v_mfma_f32_16x16x32_bf16 v[60:63], v[84:87], v[96:99], v[60:63]
	v_mfma_f32_16x16x32_bf16 v[56:59], v[88:91], v[96:99], v[56:59]
	v_mfma_f32_16x16x32_bf16 v[52:55], v[92:95], v[96:99], v[52:55]
	ds_read_b128 v[96:99], v2 offset:2048
	ds_read_b128 v[104:107], v2 offset:3072
	v_mfma_f32_16x16x32_bf16 v[48:51], v[80:83], v[100:103], v[48:51]
	v_mfma_f32_16x16x32_bf16 v[44:47], v[84:87], v[100:103], v[44:47]
	v_mfma_f32_16x16x32_bf16 v[40:43], v[88:91], v[100:103], v[40:43]
	v_mfma_f32_16x16x32_bf16 v[36:39], v[92:95], v[100:103], v[36:39]
	s_waitcnt lgkmcnt(0)
	v_mfma_f32_16x16x32_bf16 v[32:35], v[80:83], v[96:99], v[32:35]
	v_lshl_add_u64 v[0:1], v[0:1], 0, 64
	v_lshl_add_u64 v[68:69], v[68:69], 0, 64
	v_lshl_add_u64 v[70:71], v[70:71], 0, 64
	v_mfma_f32_16x16x32_bf16 v[28:31], v[84:87], v[96:99], v[28:31]
	s_cmp_eq_u32 s2, 31
	s_mov_b32 s1, s2
	v_mfma_f32_16x16x32_bf16 v[24:27], v[88:91], v[96:99], v[24:27]
	v_mfma_f32_16x16x32_bf16 v[20:23], v[92:95], v[96:99], v[20:23]
	v_mfma_f32_16x16x32_bf16 v[16:19], v[80:83], v[104:107], v[16:19]
	v_mfma_f32_16x16x32_bf16 v[12:15], v[84:87], v[104:107], v[12:15]
	v_mfma_f32_16x16x32_bf16 v[8:11], v[88:91], v[104:107], v[8:11]
	v_mfma_f32_16x16x32_bf16 v[4:7], v[92:95], v[104:107], v[4:7]
	s_cbranch_scc0 .LBB0_829
	v_add_u32_e32 v0, v75, v79
	v_add_u32_e32 v1, v75, v78
	s_waitcnt vmcnt(0)
	s_waitcnt vmcnt(0)
	s_barrier
	v_and_b32_e32 v108, 63, v77
	v_lshl_add_u32 v109, v72, 6, v108
	v_add_u32_e32 v109, s0, v109
	s_mov_b32 s101, 0x7e07e07f
	v_mul_hi_i32 v110, v109, s101
	s_movk_i32 s100, 0xdf80
	v_ashrrev_i32_e32 v110, 12, v110
	v_mad_i32_i24 v111, v110, s100, v109
	v_lshlrev_b32_e32 v110, 13, v110
	v_add_u32_e32 v110, v110, v111
	v_add_u32_e32 v110, 0xffffff80, v110
	v_lshlrev_b32_e32 v110, 12, v110
	v_lshl_add_u32 v110, v76, 8, v110
	s_lshl_b32 s101, s12, 2
	v_add_u32_e32 v110, s101, v110
	v_cmp_lt_i32_e32 vcc, 0x7f, v111
	s_and_saveexec_b64 s[98:99], vcc
	global_load_dword v114, v110, s[42:43]
	global_load_dword v115, v110, s[42:43] offset:128
	s_mov_b64 exec, s[98:99]
	ds_read_b128 v[80:83], v0 offset:25600
	ds_read_b128 v[84:87], v0 offset:24576
	ds_read_b128 v[88:91], v1 offset:44032
	ds_read_b128 v[92:95], v1 offset:43008
	ds_read_b128 v[96:99], v1 offset:41984
	ds_read_b128 v[100:103], v1 offset:40960
	s_waitcnt lgkmcnt(0)
	v_mfma_f32_16x16x32_bf16 v[68:71], v[100:103], v[84:87], v[64:67]
	v_mfma_f32_16x16x32_bf16 v[60:63], v[96:99], v[84:87], v[60:63]
	v_mfma_f32_16x16x32_bf16 v[56:59], v[92:95], v[84:87], v[56:59]
	v_mfma_f32_16x16x32_bf16 v[52:55], v[88:91], v[84:87], v[52:55]
	ds_read_b128 v[64:67], v0 offset:26624
	ds_read_b128 v[84:87], v0 offset:27648
	v_mfma_f32_16x16x32_bf16 v[48:51], v[100:103], v[80:83], v[48:51]
	v_mfma_f32_16x16x32_bf16 v[44:47], v[96:99], v[80:83], v[44:47]
	v_mfma_f32_16x16x32_bf16 v[40:43], v[92:95], v[80:83], v[40:43]
	v_mfma_f32_16x16x32_bf16 v[36:39], v[88:91], v[80:83], v[36:39]
	v_or_b32_e32 v0, s0, v73
	v_lshl_add_u32 v72, v72, 6, v0
	s_mov_b32 s0, 0x7e07e07f
	v_mul_hi_i32 v0, v72, s0
	s_waitcnt lgkmcnt(1)
	v_mfma_f32_16x16x32_bf16 v[32:35], v[100:103], v[64:67], v[32:35]
	v_lshrrev_b32_e32 v1, 31, v0
	v_ashrrev_i32_e32 v0, 12, v0
	v_add_u32_e32 v0, v0, v1
	v_mfma_f32_16x16x32_bf16 v[28:31], v[96:99], v[64:67], v[28:31]
	s_movk_i32 s0, 0xdf80
	v_mad_i32_i24 v1, v0, s0, v72
	v_cmp_lt_i32_e64 s[2:3], s54, v1
	v_mfma_f32_16x16x32_bf16 v[24:27], v[92:95], v[64:67], v[24:27]
	v_mov_b64_e32 v[74:75], 0
	s_waitcnt lgkmcnt(0)
	s_barrier
	v_mfma_f32_16x16x32_bf16 v[20:23], v[88:91], v[64:67], v[20:23]
	v_mfma_f32_16x16x32_bf16 v[16:19], v[100:103], v[84:87], v[16:19]
	v_mfma_f32_16x16x32_bf16 v[12:15], v[96:99], v[84:87], v[12:15]
	v_mfma_f32_16x16x32_bf16 v[8:11], v[92:95], v[84:87], v[8:11]
	v_mfma_f32_16x16x32_bf16 v[4:7], v[88:91], v[84:87], v[4:7]
	s_and_saveexec_b64 s[0:1], s[2:3]
	s_cbranch_execz .LBB0_832
	s_movk_i32 s4, 0x7f
	v_cmp_lt_u32_e32 vcc, s4, v1
	v_mov_b32_e32 v64, 0xffffff90
	v_mov_b32_e32 v65, 0xffffff80
	v_cndmask_b32_e64 v2, 4, 13, vcc
	v_cndmask_b32_e32 v66, v64, v65, vcc
	v_lshlrev_b32_e32 v0, v2, v0
	v_mov_b32_e32 v64, s85
	v_mov_b32_e32 v65, s43
	v_add3_u32 v0, v66, v1, v0
	v_cndmask_b32_e32 v65, v64, v65, vcc
	v_mov_b32_e32 v64, s84
	v_mov_b32_e32 v67, s42
	v_ashrrev_i32_e32 v1, 31, v0
	v_cndmask_b32_e32 v64, v64, v67, vcc
	v_lshlrev_b64 v[0:1], 12, v[0:1]
	v_lshl_add_u64 v[74:75], v[64:65], 0, v[0:1]
